# skinny GEMMs G1/G4/G5/G6: row-contiguous LDS-DMA staging + ds_read fragments instead of uncoalesced fragment loads
# speedup vs baseline: 1.0270x; 1.0270x over previous
;     __device__ __forceinline__ void prefetch4(int row, int col, Pre& p) const { p.gw = *(const u32x2*)(Zg + (size_t)row * INC + col); if (SECOND) p.pw = *(const u32x2*)(O + (size_t)row * DM + col); }
; template <int CT, class Epi> __device__ __forceinline__ void skinny_gemm(LAS unsigned char* lds, const bf16_t* A, const bf16_t* Bt, int N, int K, const Epi& E, int first) {
;     ...
;         const bf16_t* ap = A + (size_t)(NTOK_P + mt * 64 + r) * K + wave * kw + 8 * qd;
;         const bf16_t* bp = Bt + (size_t)(nt * 16 * CT + r) * K + wave * kw + 8 * qd;
;         typename Epi::Pre pre[CT / 2];
; #pragma unroll
;         for (int e = 0; e < CT / 2; ++e) { const int idx = tid + e * 512; E.prefetch4(NTOK_P + mt * 64 + idx / (4 * CT), nt * 16 * CT + (idx % (4 * CT)) * 4, pre[e]); }
;         f32x4 acc[4][CT];
; #pragma unroll
;         for (int rt = 0; rt < 4; ++rt)
; #pragma unroll
;             for (int ct = 0; ct < CT; ++ct) acc[rt][ct] = (f32x4){0.f, 0.f, 0.f, 0.f};
.LBB0_272:
	s_or_b64 exec, exec, s[0:1]
	v_or_b32_e32 v0, s11, v42
	v_lshlrev_b32_e32 v0, 11, v0
	v_lshl_add_u64 v[122:123], v[2:3], 0, v[0:1]
	v_add_co_u32_e32 v130, vcc, 0x8000, v122
	v_or_b32_e32 v38, s12, v42
	s_nop 0
	v_addc_co_u32_e32 v131, vcc, 0, v123, vcc
	v_add_co_u32_e32 v138, vcc, s73, v122
	v_ashrrev_i32_e32 v39, 31, v38
	s_nop 0
	v_addc_co_u32_e32 v139, vcc, 0, v123, vcc
	v_lshlrev_b64 v[38:39], 11, v[38:39]
	v_add_co_u32_e32 v146, vcc, s35, v122
	v_lshl_add_u64 v[154:155], v[28:29], 0, v[38:39]
	s_nop 0
	v_addc_co_u32_e32 v147, vcc, 0, v123, vcc
	v_add_co_u32_e32 v162, vcc, s85, v154
	s_nop 1
	v_addc_co_u32_e32 v163, vcc, 0, v155, vcc
	v_add_co_u32_e32 v170, vcc, s73, v154
	s_nop 1
	v_addc_co_u32_e32 v171, vcc, 0, v155, vcc
	v_add_co_u32_e32 v178, vcc, s35, v154
	s_nop 1
	v_addc_co_u32_e32 v179, vcc, 0, v155, vcc
	s_mov_b32 s100, 0x4000
	s_mov_b32 s101, 0
	v_readfirstlane_b32 s98, v184
	v_and_b32_e32 v246, 63, v184
	s_nop 1
	s_lshr_b32 s98, s98, 6
	s_lshl_b32 s98, s98, 14
	v_and_b32_e32 v247, 15, v246
	v_lshrrev_b32_e32 v248, 4, v246
	v_lshrrev_b32_e32 v249, 3, v246
	v_and_b32_e32 v246, 7, v246
	v_xor_b32_e32 v246, v246, v249
	v_sub_u32_e32 v249, v249, v247
	v_sub_u32_e32 v246, v246, v248
	v_lshlrev_b32_e32 v249, 11, v249
	v_lshl_add_u32 v240, v246, 4, v249
	v_ashrrev_i32_e32 v241, 31, v240
	v_and_b32_e32 v246, 7, v247
	v_xor_b32_e32 v246, v246, v248
	v_lshlrev_b32_e32 v246, 4, v246
	v_lshl_add_u32 v246, v247, 7, v246
	v_add_u32_e32 v242, s98, v246
	v_xor_b32_e32 v243, 64, v242
	v_add_u32_e32 v246, 0x80, v240
	v_ashrrev_i32_e32 v247, 31, v246
	s_mov_b32 m0, s98
	v_lshl_add_u64 v[236:237], v[122:123], 0, v[240:241]
	global_load_lds_dwordx4 v[236:237], off
	s_add_i32 m0, s98, 0x400
	v_lshl_add_u64 v[236:237], v[236:237], 0, s[100:101]
	global_load_lds_dwordx4 v[236:237], off
	s_add_i32 m0, s98, 0x800
	v_lshl_add_u64 v[236:237], v[236:237], 0, s[100:101]
	global_load_lds_dwordx4 v[236:237], off
	s_add_i32 m0, s98, 0xc00
	v_lshl_add_u64 v[236:237], v[236:237], 0, s[100:101]
	global_load_lds_dwordx4 v[236:237], off
	s_add_i32 m0, s98, 0x1000
	v_lshl_add_u64 v[236:237], v[236:237], 0, s[100:101]
	global_load_lds_dwordx4 v[236:237], off
	s_add_i32 m0, s98, 0x1400
	v_lshl_add_u64 v[236:237], v[236:237], 0, s[100:101]
	global_load_lds_dwordx4 v[236:237], off
	s_add_i32 m0, s98, 0x1800
	v_lshl_add_u64 v[236:237], v[236:237], 0, s[100:101]
	global_load_lds_dwordx4 v[236:237], off
	s_add_i32 m0, s98, 0x1c00
	v_lshl_add_u64 v[236:237], v[236:237], 0, s[100:101]
	global_load_lds_dwordx4 v[236:237], off
	s_add_i32 m0, s98, 0x2000
	v_lshl_add_u64 v[238:239], v[154:155], 0, v[240:241]
	global_load_lds_dwordx4 v[238:239], off
	s_add_i32 m0, s98, 0x2400
	v_lshl_add_u64 v[238:239], v[238:239], 0, s[100:101]
	global_load_lds_dwordx4 v[238:239], off
	s_add_i32 m0, s98, 0x2800
	v_lshl_add_u64 v[238:239], v[238:239], 0, s[100:101]
	global_load_lds_dwordx4 v[238:239], off
	s_add_i32 m0, s98, 0x2c00
	v_lshl_add_u64 v[238:239], v[238:239], 0, s[100:101]
	global_load_lds_dwordx4 v[238:239], off
	s_add_i32 m0, s98, 0x3000
	v_lshl_add_u64 v[238:239], v[238:239], 0, s[100:101]
	global_load_lds_dwordx4 v[238:239], off
	s_add_i32 m0, s98, 0x3400
	v_lshl_add_u64 v[238:239], v[238:239], 0, s[100:101]
	global_load_lds_dwordx4 v[238:239], off
	s_add_i32 m0, s98, 0x3800
	v_lshl_add_u64 v[238:239], v[238:239], 0, s[100:101]
	global_load_lds_dwordx4 v[238:239], off
	s_add_i32 m0, s98, 0x3c00
	v_lshl_add_u64 v[238:239], v[238:239], 0, s[100:101]
	global_load_lds_dwordx4 v[238:239], off
	s_waitcnt vmcnt(0)
	ds_read_b128 v[38:41], v242
	ds_read_b128 v[62:65], v242 offset:2048
	ds_read_b128 v[70:73], v242 offset:4096
	ds_read_b128 v[78:81], v242 offset:6144
	ds_read_b128 v[58:61], v243
	ds_read_b128 v[66:69], v243 offset:2048
	ds_read_b128 v[74:77], v243 offset:4096
	ds_read_b128 v[82:85], v243 offset:6144
	ds_read_b128 v[86:89], v242 offset:8192
	ds_read_b128 v[94:97], v242 offset:10240
	ds_read_b128 v[102:105], v242 offset:12288
	ds_read_b128 v[110:113], v242 offset:14336
	ds_read_b128 v[90:93], v243 offset:8192
	ds_read_b128 v[98:101], v243 offset:10240
	ds_read_b128 v[106:109], v243 offset:12288
	ds_read_b128 v[114:117], v243 offset:14336
	s_waitcnt lgkmcnt(0)
	s_mov_b32 m0, s98
	v_lshl_add_u64 v[236:237], v[122:123], 0, v[246:247]
	global_load_lds_dwordx4 v[236:237], off
	s_add_i32 m0, s98, 0x400
	v_lshl_add_u64 v[236:237], v[236:237], 0, s[100:101]
	global_load_lds_dwordx4 v[236:237], off
	s_add_i32 m0, s98, 0x800
	v_lshl_add_u64 v[236:237], v[236:237], 0, s[100:101]
	global_load_lds_dwordx4 v[236:237], off
	s_add_i32 m0, s98, 0xc00
	v_lshl_add_u64 v[236:237], v[236:237], 0, s[100:101]
	global_load_lds_dwordx4 v[236:237], off
	s_add_i32 m0, s98, 0x1000
	v_lshl_add_u64 v[236:237], v[236:237], 0, s[100:101]
	global_load_lds_dwordx4 v[236:237], off
	s_add_i32 m0, s98, 0x1400
	v_lshl_add_u64 v[236:237], v[236:237], 0, s[100:101]
	global_load_lds_dwordx4 v[236:237], off
	s_add_i32 m0, s98, 0x1800
	v_lshl_add_u64 v[236:237], v[236:237], 0, s[100:101]
	global_load_lds_dwordx4 v[236:237], off
	s_add_i32 m0, s98, 0x1c00
	v_lshl_add_u64 v[236:237], v[236:237], 0, s[100:101]
	global_load_lds_dwordx4 v[236:237], off
	s_add_i32 m0, s98, 0x2000
	v_lshl_add_u64 v[238:239], v[154:155], 0, v[246:247]
	global_load_lds_dwordx4 v[238:239], off
	s_add_i32 m0, s98, 0x2400
	v_lshl_add_u64 v[238:239], v[238:239], 0, s[100:101]
	global_load_lds_dwordx4 v[238:239], off
	s_add_i32 m0, s98, 0x2800
	v_lshl_add_u64 v[238:239], v[238:239], 0, s[100:101]
	global_load_lds_dwordx4 v[238:239], off
	s_add_i32 m0, s98, 0x2c00
	v_lshl_add_u64 v[238:239], v[238:239], 0, s[100:101]
; #define LAS __attribute__((address_space(3)))
; template <int CT, class Epi> __device__ __forceinline__ void skinny_gemm(LAS unsigned char* lds, const bf16_t* A, const bf16_t* Bt, int N, int K, const Epi& E, int first) {
;     ...
;         if (nsteps >= 4) {
; #pragma unroll 1
;             for (int s0 = 0; s0 < nsteps; s0 += 4) SKINNY_GROUP(4, s0);
;         } else SKINNY_GROUP(2, 0);
;     ...
; #pragma unroll
;         for (int rt = 0; rt < 4; ++rt)
; #pragma unroll
;             for (int ct = 0; ct < CT; ++ct) *(LAS f32x4*)(red + wave * (64 * 16 * CT) + (rt * 16 + r) * (16 * CT) + ct * 16 + 4 * qd) = acc[rt][ct];
	global_load_lds_dwordx4 v[238:239], off
	s_add_i32 m0, s98, 0x3000
	v_lshl_add_u64 v[238:239], v[238:239], 0, s[100:101]
	global_load_lds_dwordx4 v[238:239], off
	s_add_i32 m0, s98, 0x3400
	v_lshl_add_u64 v[238:239], v[238:239], 0, s[100:101]
	global_load_lds_dwordx4 v[238:239], off
	s_add_i32 m0, s98, 0x3800
	v_lshl_add_u64 v[238:239], v[238:239], 0, s[100:101]
	global_load_lds_dwordx4 v[238:239], off
	s_add_i32 m0, s98, 0x3c00
	v_lshl_add_u64 v[238:239], v[238:239], 0, s[100:101]
	global_load_lds_dwordx4 v[238:239], off
	s_nop 0
	s_nop 0
	s_nop 0
	s_nop 0
	s_nop 0
	s_nop 0
	s_nop 0
	s_nop 0
	s_nop 0
	s_nop 0
	s_nop 0
	s_nop 0
	s_nop 0
	s_nop 0
	s_nop 0
	v_mfma_f32_16x16x32_bf16 v[190:193], v[86:89], v[38:41], 0
	v_mfma_f32_16x16x32_bf16 v[194:197], v[94:97], v[38:41], 0
	v_mfma_f32_16x16x32_bf16 v[198:201], v[102:105], v[38:41], 0
	v_mfma_f32_16x16x32_bf16 v[38:41], v[110:113], v[38:41], 0
	v_mfma_f32_16x16x32_bf16 v[202:205], v[86:89], v[62:65], 0
	v_mfma_f32_16x16x32_bf16 v[206:209], v[94:97], v[62:65], 0
	v_mfma_f32_16x16x32_bf16 v[220:223], v[102:105], v[62:65], 0
	v_mfma_f32_16x16x32_bf16 v[62:65], v[110:113], v[62:65], 0
	v_mfma_f32_16x16x32_bf16 v[224:227], v[86:89], v[70:73], 0
	v_mfma_f32_16x16x32_bf16 v[228:231], v[94:97], v[70:73], 0
	v_mfma_f32_16x16x32_bf16 v[232:235], v[102:105], v[70:73], 0
	v_mfma_f32_16x16x32_bf16 v[70:73], v[110:113], v[70:73], 0
	v_mfma_f32_16x16x32_bf16 v[86:89], v[86:89], v[78:81], 0
	v_mfma_f32_16x16x32_bf16 v[94:97], v[94:97], v[78:81], 0
	v_mfma_f32_16x16x32_bf16 v[102:105], v[102:105], v[78:81], 0
	v_mfma_f32_16x16x32_bf16 v[78:81], v[110:113], v[78:81], 0
	v_mfma_f32_16x16x32_bf16 v[38:41], v[114:117], v[58:61], v[38:41]
	v_mfma_f32_16x16x32_bf16 v[110:113], v[90:93], v[58:61], v[190:193]
	v_mfma_f32_16x16x32_bf16 v[190:193], v[98:101], v[58:61], v[194:197]
	v_mfma_f32_16x16x32_bf16 v[194:197], v[106:109], v[58:61], v[198:201]
	v_mfma_f32_16x16x32_bf16 v[58:61], v[90:93], v[66:69], v[202:205]
	v_mfma_f32_16x16x32_bf16 v[198:201], v[98:101], v[66:69], v[206:209]
	v_mfma_f32_16x16x32_bf16 v[202:205], v[106:109], v[66:69], v[220:223]
	v_mfma_f32_16x16x32_bf16 v[62:65], v[114:117], v[66:69], v[62:65]
	v_mfma_f32_16x16x32_bf16 v[66:69], v[90:93], v[74:77], v[224:227]
	v_mfma_f32_16x16x32_bf16 v[206:209], v[98:101], v[74:77], v[228:231]
	v_mfma_f32_16x16x32_bf16 v[220:223], v[106:109], v[74:77], v[232:235]
	v_mfma_f32_16x16x32_bf16 v[70:73], v[114:117], v[74:77], v[70:73]
	v_mfma_f32_16x16x32_bf16 v[74:77], v[90:93], v[82:85], v[86:89]
	v_mfma_f32_16x16x32_bf16 v[86:89], v[98:101], v[82:85], v[94:97]
	v_mfma_f32_16x16x32_bf16 v[90:93], v[106:109], v[82:85], v[102:105]
	v_mfma_f32_16x16x32_bf16 v[78:81], v[114:117], v[82:85], v[78:81]
	s_waitcnt vmcnt(0)
	ds_read_b128 v[118:121], v242
	ds_read_b128 v[126:129], v242 offset:2048
	ds_read_b128 v[134:137], v242 offset:4096
	ds_read_b128 v[142:145], v242 offset:6144
	ds_read_b128 v[122:125], v243
	ds_read_b128 v[130:133], v243 offset:2048
	ds_read_b128 v[138:141], v243 offset:4096
	ds_read_b128 v[146:149], v243 offset:6144
	ds_read_b128 v[150:153], v242 offset:8192
	ds_read_b128 v[158:161], v242 offset:10240
	ds_read_b128 v[166:169], v242 offset:12288
	ds_read_b128 v[174:177], v242 offset:14336
	ds_read_b128 v[154:157], v243 offset:8192
	ds_read_b128 v[162:165], v243 offset:10240
	ds_read_b128 v[170:173], v243 offset:12288
	ds_read_b128 v[178:181], v243 offset:14336
	s_waitcnt lgkmcnt(0)
	v_mfma_f32_16x16x32_bf16 v[38:41], v[174:177], v[118:121], v[38:41]
	v_mfma_f32_16x16x32_bf16 v[82:85], v[150:153], v[118:121], v[110:113]
	v_mfma_f32_16x16x32_bf16 v[94:97], v[158:161], v[118:121], v[190:193]
	v_mfma_f32_16x16x32_bf16 v[98:101], v[166:169], v[118:121], v[194:197]
	v_mfma_f32_16x16x32_bf16 v[58:61], v[150:153], v[126:129], v[58:61]
	v_mfma_f32_16x16x32_bf16 v[102:105], v[158:161], v[126:129], v[198:201]
	v_mfma_f32_16x16x32_bf16 v[106:109], v[166:169], v[126:129], v[202:205]
	v_mfma_f32_16x16x32_bf16 v[62:65], v[174:177], v[126:129], v[62:65]
	v_mfma_f32_16x16x32_bf16 v[66:69], v[150:153], v[134:137], v[66:69]
	v_mfma_f32_16x16x32_bf16 v[110:113], v[158:161], v[134:137], v[206:209]
	v_mfma_f32_16x16x32_bf16 v[114:117], v[166:169], v[134:137], v[220:223]
	v_mfma_f32_16x16x32_bf16 v[70:73], v[174:177], v[134:137], v[70:73]
	v_mfma_f32_16x16x32_bf16 v[74:77], v[150:153], v[142:145], v[74:77]
	v_mfma_f32_16x16x32_bf16 v[86:89], v[158:161], v[142:145], v[86:89]
	v_mfma_f32_16x16x32_bf16 v[90:93], v[166:169], v[142:145], v[90:93]
	v_mfma_f32_16x16x32_bf16 v[78:81], v[174:177], v[142:145], v[78:81]
	v_mfma_f32_16x16x32_bf16 v[38:41], v[178:181], v[122:125], v[38:41]
	v_mfma_f32_16x16x32_bf16 v[82:85], v[154:157], v[122:125], v[82:85]
	v_mfma_f32_16x16x32_bf16 v[94:97], v[162:165], v[122:125], v[94:97]
	v_mfma_f32_16x16x32_bf16 v[98:101], v[170:173], v[122:125], v[98:101]
	v_mfma_f32_16x16x32_bf16 v[58:61], v[154:157], v[130:133], v[58:61]
	v_mfma_f32_16x16x32_bf16 v[102:105], v[162:165], v[130:133], v[102:105]
	v_mfma_f32_16x16x32_bf16 v[106:109], v[170:173], v[130:133], v[106:109]
	v_mfma_f32_16x16x32_bf16 v[62:65], v[178:181], v[130:133], v[62:65]
	v_mfma_f32_16x16x32_bf16 v[66:69], v[154:157], v[138:141], v[66:69]
	v_mfma_f32_16x16x32_bf16 v[110:113], v[162:165], v[138:141], v[110:113]
	v_mfma_f32_16x16x32_bf16 v[114:117], v[170:173], v[138:141], v[114:117]
	v_mfma_f32_16x16x32_bf16 v[70:73], v[178:181], v[138:141], v[70:73]
	v_mfma_f32_16x16x32_bf16 v[74:77], v[154:157], v[146:149], v[74:77]
	v_mfma_f32_16x16x32_bf16 v[86:89], v[162:165], v[146:149], v[86:89]
	v_mfma_f32_16x16x32_bf16 v[90:93], v[170:173], v[146:149], v[90:93]
	v_mfma_f32_16x16x32_bf16 v[78:81], v[178:181], v[146:149], v[78:81]
	ds_write_b128 v57, v[82:85]
	ds_write_b128 v57, v[94:97] offset:64
	ds_write_b128 v57, v[98:101] offset:128
	ds_write_b128 v57, v[38:41] offset:192
	ds_write_b128 v57, v[58:61] offset:4096
	ds_write_b128 v57, v[102:105] offset:4160
	ds_write_b128 v57, v[106:109] offset:4224
	ds_write_b128 v57, v[62:65] offset:4288
	ds_write_b128 v57, v[66:69] offset:8192
	ds_write_b128 v57, v[110:113] offset:8256
	ds_write_b128 v57, v[114:117] offset:8320
	ds_write_b128 v57, v[70:73] offset:8384
	ds_write_b128 v57, v[74:77] offset:12288
	ds_write_b128 v57, v[86:89] offset:12352
	ds_write_b128 v57, v[90:93] offset:12416
	ds_write_b128 v57, v[78:81] offset:12480
	s_waitcnt lgkmcnt(0)
	s_barrier
; #define LAS __attribute__((address_space(3)))
; __device__ __forceinline__ float sigm(float x) { return __builtin_amdgcn_rcpf(1.f + __builtin_amdgcn_exp2f(-LOG2E * x)); }
;     __device__ __forceinline__ void apply4(int row, int col, f32x4 v, const Pre& p) const {
;         const float rs = rsqrtf(p.ssv * (1.f / DM) + EPS); v = v * rs;
;         if (col >= ZG) { const f32x4 b = p.b; v = (f32x4){sigm(v[0] + b[0]), sigm(v[1] + b[1]), sigm(v[2] + b[2]), sigm(v[3] + b[3])}; }
; template <int CT, class Epi> __device__ __forceinline__ void skinny_gemm(LAS unsigned char* lds, const bf16_t* A, const bf16_t* Bt, int N, int K, const Epi& E, int first) {
;     ...
;         for (int e = 0; e < CT / 2; ++e) { const int idx = tid + e * 512, row = idx / (4 * CT), c4 = idx % (4 * CT);
;             f32x4 v = *(const LAS f32x4*)(red + row * (16 * CT) + c4 * 4);
; #pragma unroll
;             for (int w = 1; w < 8; ++w) v = v + *(const LAS f32x4*)(red + w * (64 * 16 * CT) + row * (16 * CT) + c4 * 4);
;             E.apply4(NTOK_P + mt * 64 + row, nt * 16 * CT + c4 * 4, v, pre[e]); }
	ds_read_b128 v[38:41], v47
	ds_read_b128 v[58:61], v47 offset:16384
	ds_read_b128 v[62:65], v47 offset:32768
	ds_read_b128 v[66:69], v47 offset:49152
	v_fmamk_f32 v0, v35, 0x3a800000, v185
	v_mul_f32_e32 v33, 0x4b800000, v0
	s_waitcnt lgkmcnt(2)
	v_pk_add_f32 v[40:41], v[40:41], v[60:61]
	v_pk_add_f32 v[58:59], v[38:39], v[58:59]
	s_waitcnt lgkmcnt(1)
	v_pk_add_f32 v[60:61], v[40:41], v[64:65]
	ds_read_b128 v[38:41], v48
	v_pk_add_f32 v[62:63], v[58:59], v[62:63]
	s_waitcnt lgkmcnt(1)
	v_pk_add_f32 v[64:65], v[60:61], v[68:69]
	ds_read_b128 v[58:61], v49
	v_pk_add_f32 v[66:67], v[62:63], v[66:67]
	v_cmp_gt_f32_e32 vcc, s86, v0
	s_waitcnt lgkmcnt(1)
	v_pk_add_f32 v[40:41], v[64:65], v[40:41]
	ds_read_b128 v[62:65], v50
	v_pk_add_f32 v[38:39], v[66:67], v[38:39]
	v_cndmask_b32_e32 v0, v0, v33, vcc
	s_waitcnt lgkmcnt(1)
	v_pk_add_f32 v[60:61], v[40:41], v[60:61]
	v_pk_add_f32 v[58:59], v[38:39], v[58:59]
	ds_read_b128 v[38:41], v51
	v_rsq_f32_e32 v0, v0
	s_waitcnt lgkmcnt(1)
	v_pk_add_f32 v[60:61], v[60:61], v[64:65]
	v_pk_add_f32 v[58:59], v[58:59], v[62:63]
	v_mul_f32_e32 v33, 0x45800000, v0
	s_waitcnt lgkmcnt(0)
	v_pk_add_f32 v[40:41], v[60:61], v[40:41]
	v_pk_add_f32 v[58:59], v[58:59], v[38:39]
	v_cndmask_b32_e32 v0, v0, v33, vcc
	v_pk_mul_f32 v[38:39], v[0:1], v[40:41] op_sel_hi:[0,1]
	v_pk_mul_f32 v[40:41], v[0:1], v[58:59] op_sel_hi:[0,1]
	s_and_saveexec_b64 s[0:1], s[6:7]
	s_cbranch_execz .LBB0_274
	v_add_f32_e32 v0, v24, v40
	v_mul_f32_e32 v0, 0xbfb8aa3b, v0
	v_add_f32_e32 v24, v25, v41
	v_exp_f32_e32 v0, v0
	v_mul_f32_e32 v24, 0xbfb8aa3b, v24
	v_exp_f32_e32 v24, v24
	v_add_f32_e32 v25, v27, v39
	v_add_f32_e32 v0, 1.0, v0
	v_rcp_f32_e32 v40, v0
	v_add_f32_e32 v0, 1.0, v24
	v_add_f32_e32 v24, v26, v38
	v_mul_f32_e32 v24, 0xbfb8aa3b, v24
	v_exp_f32_e32 v24, v24
	v_mul_f32_e32 v25, 0xbfb8aa3b, v25
	v_exp_f32_e32 v25, v25
	v_rcp_f32_e32 v41, v0
	v_add_f32_e32 v0, 1.0, v24
	v_rcp_f32_e32 v38, v0
	v_add_f32_e32 v0, 1.0, v25
	v_rcp_f32_e32 v39, v0

;     __device__ __forceinline__ void prefetch4(int row, int col, Pre& p) const { p.gw = *(const u32x2*)(Zg + (size_t)row * INC + col); if (SECOND) p.pw = *(const u32x2*)(O + (size_t)row * DM + col); }
; template <int CT, class Epi> __device__ __forceinline__ void skinny_gemm(LAS unsigned char* lds, const bf16_t* A, const bf16_t* Bt, int N, int K, const Epi& E, int first) {
;     ...
;         const bf16_t* ap = A + (size_t)(NTOK_P + mt * 64 + r) * K + wave * kw + 8 * qd;
;         const bf16_t* bp = Bt + (size_t)(nt * 16 * CT + r) * K + wave * kw + 8 * qd;
;         typename Epi::Pre pre[CT / 2];
; #pragma unroll
;         for (int e = 0; e < CT / 2; ++e) { const int idx = tid + e * 512; E.prefetch4(NTOK_P + mt * 64 + idx / (4 * CT), nt * 16 * CT + (idx % (4 * CT)) * 4, pre[e]); }
;         f32x4 acc[4][CT];
; #pragma unroll
;         for (int rt = 0; rt < 4; ++rt)
; #pragma unroll
;             for (int ct = 0; ct < CT; ++ct) acc[rt][ct] = (f32x4){0.f, 0.f, 0.f, 0.f};
.LBB0_800:
	s_and_b32 s0, s6, 0x1c0
	s_bitset1_b32 s0, 14
	v_or_b32_e32 v0, s0, v26
	v_lshlrev_b32_e32 v0, 11, v0
	v_lshl_add_u64 v[84:85], v[2:3], 0, v[0:1]
	v_add_co_u32_e32 v92, vcc, s85, v84
	s_and_b32 s1, s7, 0xffffffe0
	s_nop 0
	v_addc_co_u32_e32 v93, vcc, 0, v85, vcc
	v_or_b32_e32 v32, s1, v26
	v_add_co_u32_e32 v100, vcc, s73, v84
	v_ashrrev_i32_e32 v33, 31, v32
	v_add_u32_e32 v22, s0, v27
	v_addc_co_u32_e32 v101, vcc, 0, v85, vcc
	s_and_b32 s0, s8, 0x3ffffff8
	v_ashrrev_i32_e32 v23, 31, v22
	v_lshlrev_b64 v[32:33], 11, v[32:33]
	v_add_co_u32_e32 v108, vcc, s35, v84
	v_add_lshl_u32 v34, s0, v28, 2
	v_lshlrev_b64 v[24:25], 11, v[22:23]
	v_lshl_add_u64 v[116:117], v[20:21], 0, v[32:33]
	v_addc_co_u32_e32 v109, vcc, 0, v85, vcc
	v_lshl_add_u64 v[36:37], s[30:31], 0, v[24:25]
	v_ashrrev_i32_e32 v35, 31, v34
	v_add_co_u32_e32 v124, vcc, s85, v116
	v_lshl_add_u64 v[34:35], v[34:35], 1, v[36:37]
	s_nop 0
	v_addc_co_u32_e32 v125, vcc, 0, v117, vcc
	global_load_dwordx2 v[140:141], v[34:35], off
	s_nop 0
	s_mov_b32 s100, 0x4000
	s_mov_b32 s101, 0
	v_readfirstlane_b32 s98, v184
	v_and_b32_e32 v246, 63, v184
	s_nop 1
	s_lshr_b32 s98, s98, 6
	s_lshl_b32 s99, s98, 12
	s_add_i32 s99, s99, 0x10000
	s_lshl_b32 s98, s98, 13
	v_and_b32_e32 v247, 15, v246
	v_lshrrev_b32_e32 v248, 4, v246
	v_lshrrev_b32_e32 v249, 3, v246
	v_and_b32_e32 v246, 7, v246
	v_xor_b32_e32 v246, v246, v249
	v_sub_u32_e32 v249, v249, v247
	v_sub_u32_e32 v246, v246, v248
	v_lshlrev_b32_e32 v249, 11, v249
	v_lshl_add_u32 v240, v246, 4, v249
	v_ashrrev_i32_e32 v241, 31, v240
	v_and_b32_e32 v246, 7, v247
	v_xor_b32_e32 v246, v246, v248
	v_lshlrev_b32_e32 v246, 4, v246
	v_lshl_add_u32 v246, v247, 7, v246
	v_add_u32_e32 v242, s98, v246
	v_xor_b32_e32 v243, 64, v242
	v_add_u32_e32 v244, s99, v246
	v_xor_b32_e32 v245, 64, v244
	v_add_u32_e32 v246, 0x80, v240
	v_ashrrev_i32_e32 v247, 31, v246
	s_mov_b32 m0, s98
	v_lshl_add_u64 v[236:237], v[84:85], 0, v[240:241]
	global_load_lds_dwordx4 v[236:237], off
	s_add_i32 m0, s98, 0x400
	v_lshl_add_u64 v[236:237], v[236:237], 0, s[100:101]
	global_load_lds_dwordx4 v[236:237], off
	s_add_i32 m0, s98, 0x800
	v_lshl_add_u64 v[236:237], v[236:237], 0, s[100:101]
	global_load_lds_dwordx4 v[236:237], off
	s_add_i32 m0, s98, 0xc00
	v_lshl_add_u64 v[236:237], v[236:237], 0, s[100:101]
	global_load_lds_dwordx4 v[236:237], off
	s_add_i32 m0, s98, 0x1000
	v_lshl_add_u64 v[236:237], v[236:237], 0, s[100:101]
	global_load_lds_dwordx4 v[236:237], off
	s_add_i32 m0, s98, 0x1400
	v_lshl_add_u64 v[236:237], v[236:237], 0, s[100:101]
	global_load_lds_dwordx4 v[236:237], off
	s_add_i32 m0, s98, 0x1800
	v_lshl_add_u64 v[236:237], v[236:237], 0, s[100:101]
	global_load_lds_dwordx4 v[236:237], off
	s_add_i32 m0, s98, 0x1c00
	v_lshl_add_u64 v[236:237], v[236:237], 0, s[100:101]
	global_load_lds_dwordx4 v[236:237], off
	s_mov_b32 m0, s99
	v_lshl_add_u64 v[238:239], v[116:117], 0, v[240:241]
	global_load_lds_dwordx4 v[238:239], off
	s_add_i32 m0, s99, 0x400
	v_lshl_add_u64 v[238:239], v[238:239], 0, s[100:101]
	global_load_lds_dwordx4 v[238:239], off
	s_add_i32 m0, s99, 0x800
	v_lshl_add_u64 v[238:239], v[238:239], 0, s[100:101]
	global_load_lds_dwordx4 v[238:239], off
	s_add_i32 m0, s99, 0xc00
	v_lshl_add_u64 v[238:239], v[238:239], 0, s[100:101]
	global_load_lds_dwordx4 v[238:239], off
	s_waitcnt vmcnt(0)
	ds_read_b128 v[32:35], v242
	ds_read_b128 v[40:43], v242 offset:2048
	ds_read_b128 v[48:51], v242 offset:4096
	ds_read_b128 v[56:59], v242 offset:6144
	ds_read_b128 v[36:39], v243
	ds_read_b128 v[44:47], v243 offset:2048
	ds_read_b128 v[52:55], v243 offset:4096
	ds_read_b128 v[60:63], v243 offset:6144
	ds_read_b128 v[64:67], v244
	ds_read_b128 v[72:75], v244 offset:2048
	ds_read_b128 v[68:71], v245
	ds_read_b128 v[76:79], v245 offset:2048
	s_waitcnt lgkmcnt(0)
	s_mov_b32 m0, s98
	v_lshl_add_u64 v[236:237], v[84:85], 0, v[246:247]
	global_load_lds_dwordx4 v[236:237], off
	s_add_i32 m0, s98, 0x400
	v_lshl_add_u64 v[236:237], v[236:237], 0, s[100:101]
	global_load_lds_dwordx4 v[236:237], off
	s_add_i32 m0, s98, 0x800
	v_lshl_add_u64 v[236:237], v[236:237], 0, s[100:101]
	global_load_lds_dwordx4 v[236:237], off
	s_add_i32 m0, s98, 0xc00
	v_lshl_add_u64 v[236:237], v[236:237], 0, s[100:101]
	global_load_lds_dwordx4 v[236:237], off
	s_add_i32 m0, s98, 0x1000
	v_lshl_add_u64 v[236:237], v[236:237], 0, s[100:101]
	global_load_lds_dwordx4 v[236:237], off
	s_add_i32 m0, s98, 0x1400
	v_lshl_add_u64 v[236:237], v[236:237], 0, s[100:101]
	global_load_lds_dwordx4 v[236:237], off
	s_add_i32 m0, s98, 0x1800
	v_lshl_add_u64 v[236:237], v[236:237], 0, s[100:101]
	global_load_lds_dwordx4 v[236:237], off
	s_add_i32 m0, s98, 0x1c00
	v_lshl_add_u64 v[236:237], v[236:237], 0, s[100:101]
	global_load_lds_dwordx4 v[236:237], off
	s_mov_b32 m0, s99
	v_lshl_add_u64 v[238:239], v[116:117], 0, v[246:247]
	global_load_lds_dwordx4 v[238:239], off
	s_add_i32 m0, s99, 0x400
	v_lshl_add_u64 v[238:239], v[238:239], 0, s[100:101]
	global_load_lds_dwordx4 v[238:239], off
	s_add_i32 m0, s99, 0x800
	v_lshl_add_u64 v[238:239], v[238:239], 0, s[100:101]
	global_load_lds_dwordx4 v[238:239], off
	s_add_i32 m0, s99, 0xc00
	v_lshl_add_u64 v[238:239], v[238:239], 0, s[100:101]
	global_load_lds_dwordx4 v[238:239], off
	s_nop 0
	s_nop 0
	s_nop 0
	s_nop 0
	s_nop 0
	s_nop 0
	s_nop 0
	s_nop 0
	s_nop 0
	s_nop 0
	s_nop 0
	v_mfma_f32_16x16x32_bf16 v[128:131], v[64:67], v[32:35], 0
	v_mfma_f32_16x16x32_bf16 v[32:35], v[72:75], v[32:35], 0
	v_mfma_f32_16x16x32_bf16 v[132:135], v[64:67], v[40:43], 0
	v_mfma_f32_16x16x32_bf16 v[40:43], v[72:75], v[40:43], 0
	v_mfma_f32_16x16x32_bf16 v[136:139], v[64:67], v[48:51], 0
	v_mfma_f32_16x16x32_bf16 v[48:51], v[72:75], v[48:51], 0
	v_mfma_f32_16x16x32_bf16 v[64:67], v[64:67], v[56:59], 0
	v_mfma_f32_16x16x32_bf16 v[56:59], v[72:75], v[56:59], 0
	v_mfma_f32_16x16x32_bf16 v[72:75], v[68:71], v[36:39], v[128:131]
	v_mfma_f32_16x16x32_bf16 v[32:35], v[76:79], v[36:39], v[32:35]
	v_mfma_f32_16x16x32_bf16 v[36:39], v[68:71], v[44:47], v[132:135]
	v_mfma_f32_16x16x32_bf16 v[40:43], v[76:79], v[44:47], v[40:43]
	v_mfma_f32_16x16x32_bf16 v[44:47], v[68:71], v[52:55], v[136:139]
	v_mfma_f32_16x16x32_bf16 v[48:51], v[76:79], v[52:55], v[48:51]
	v_mfma_f32_16x16x32_bf16 v[52:55], v[68:71], v[60:63], v[64:67]
	v_mfma_f32_16x16x32_bf16 v[56:59], v[76:79], v[60:63], v[56:59]
	s_waitcnt vmcnt(0)
; #define LAS __attribute__((address_space(3)))
; __device__ __forceinline__ float bflo(unsigned w) { return __uint_as_float(w << 16); }
; __device__ __forceinline__ float bfhi(unsigned w) { return __uint_as_float(w & 0xffff0000u); }
; __device__ __forceinline__ unsigned pk2(float lo, float hi) { return pg8::cvt_pk_bf16(lo, hi); }
;     __device__ __forceinline__ void apply4(int row, int col, f32x4 v, const Pre& p) const {
;         const size_t off = (size_t)row * DM + col; const u32x2 bw = p.bw;
;         v = v + (f32x4){bflo(bw.x), bfhi(bw.x), bflo(bw.y), bfhi(bw.y)};
;         if (Xf) *(f32x4*)(Xf + off) = v;
;         if (XB) { u32x2 w; w.x = pk2(v[0], v[1]); w.y = pk2(v[2], v[3]); *(u32x2*)(XB + off) = w; }
;         if (ss) { float sq = (v[0] * v[0] + v[1] * v[1]) + (v[2] * v[2] + v[3] * v[3]); sq += __shfl_xor(sq, 1); sq += __shfl_xor(sq, 2); sq += __shfl_xor(sq, 4); if ((threadIdx.x & 7) == 0) atomicAdd(ss + row, sq); }
;     }
; template <int CT, class Epi> __device__ __forceinline__ void skinny_gemm(LAS unsigned char* lds, const bf16_t* A, const bf16_t* Bt, int N, int K, const Epi& E, int first) {
;     ...
;         if (nsteps >= 4) {
; #pragma unroll 1
;             for (int s0 = 0; s0 < nsteps; s0 += 4) SKINNY_GROUP(4, s0);
;         } else SKINNY_GROUP(2, 0);
;     ...
; #pragma unroll
;         for (int rt = 0; rt < 4; ++rt)
; #pragma unroll
;             for (int ct = 0; ct < CT; ++ct) *(LAS f32x4*)(red + wave * (64 * 16 * CT) + (rt * 16 + r) * (16 * CT) + ct * 16 + 4 * qd) = acc[rt][ct];
;         __syncthreads();
; #pragma unroll
;         for (int e = 0; e < CT / 2; ++e) { const int idx = tid + e * 512, row = idx / (4 * CT), c4 = idx % (4 * CT);
;             f32x4 v = *(const LAS f32x4*)(red + row * (16 * CT) + c4 * 4);
; #pragma unroll
;             for (int w = 1; w < 8; ++w) v = v + *(const LAS f32x4*)(red + w * (64 * 16 * CT) + row * (16 * CT) + c4 * 4);
;             E.apply4(NTOK_P + mt * 64 + row, nt * 16 * CT + c4 * 4, v, pre[e]); }
	ds_read_b128 v[80:83], v242
	ds_read_b128 v[88:91], v242 offset:2048
	ds_read_b128 v[96:99], v242 offset:4096
	ds_read_b128 v[104:107], v242 offset:6144
	ds_read_b128 v[84:87], v243
	ds_read_b128 v[92:95], v243 offset:2048
	ds_read_b128 v[100:103], v243 offset:4096
	ds_read_b128 v[108:111], v243 offset:6144
	ds_read_b128 v[112:115], v244
	ds_read_b128 v[120:123], v244 offset:2048
	ds_read_b128 v[116:119], v245
	ds_read_b128 v[124:127], v245 offset:2048
	s_waitcnt lgkmcnt(0)
	v_mfma_f32_16x16x32_bf16 v[60:63], v[112:115], v[80:83], v[72:75]
	v_mfma_f32_16x16x32_bf16 v[32:35], v[120:123], v[80:83], v[32:35]
	v_mfma_f32_16x16x32_bf16 v[36:39], v[112:115], v[88:91], v[36:39]
	v_mfma_f32_16x16x32_bf16 v[40:43], v[120:123], v[88:91], v[40:43]
	v_mfma_f32_16x16x32_bf16 v[44:47], v[112:115], v[96:99], v[44:47]
	v_mfma_f32_16x16x32_bf16 v[48:51], v[120:123], v[96:99], v[48:51]
	v_mfma_f32_16x16x32_bf16 v[52:55], v[112:115], v[104:107], v[52:55]
	v_mfma_f32_16x16x32_bf16 v[56:59], v[120:123], v[104:107], v[56:59]
	v_mfma_f32_16x16x32_bf16 v[60:63], v[116:119], v[84:87], v[60:63]
	v_mfma_f32_16x16x32_bf16 v[32:35], v[124:127], v[84:87], v[32:35]
	v_mfma_f32_16x16x32_bf16 v[36:39], v[116:119], v[92:95], v[36:39]
	v_mfma_f32_16x16x32_bf16 v[40:43], v[124:127], v[92:95], v[40:43]
	v_mfma_f32_16x16x32_bf16 v[44:47], v[116:119], v[100:103], v[44:47]
	v_mfma_f32_16x16x32_bf16 v[48:51], v[124:127], v[100:103], v[48:51]
	v_mfma_f32_16x16x32_bf16 v[52:55], v[116:119], v[108:111], v[52:55]
	v_mfma_f32_16x16x32_bf16 v[56:59], v[124:127], v[108:111], v[56:59]
	ds_write_b128 v31, v[60:63]
	s_nop 0
	ds_write_b128 v31, v[32:35] offset:64
	ds_write_b128 v31, v[36:39] offset:2048
	ds_write_b128 v31, v[40:43] offset:2112
	ds_write_b128 v31, v[44:47] offset:4096
	ds_write_b128 v31, v[48:51] offset:4160
	ds_write_b128 v31, v[52:55] offset:6144
	ds_write_b128 v31, v[56:59] offset:6208
	s_waitcnt lgkmcnt(0)
	s_barrier
	ds_read_b128 v[32:35], v30
	ds_read_b128 v[36:39], v30 offset:8192
	v_add_u32_e32 v40, s1, v29
	v_ashrrev_i32_e32 v41, 31, v40
	v_lshlrev_b32_e32 v42, 16, v140
	v_and_b32_e32 v43, 0xffff0000, v140
	s_waitcnt lgkmcnt(0)
	v_pk_add_f32 v[38:39], v[34:35], v[38:39]
	v_pk_add_f32 v[36:37], v[32:33], v[36:37]
	ds_read_b128 v[32:35], v30 offset:16384
	v_lshlrev_b32_e32 v44, 16, v141
	v_and_b32_e32 v45, 0xffff0000, v141
	v_lshl_add_u64 v[24:25], s[36:37], 0, v[24:25]
	v_lshl_add_u64 v[24:25], v[40:41], 1, v[24:25]
	s_waitcnt lgkmcnt(0)
	v_pk_add_f32 v[38:39], v[38:39], v[34:35]
	v_pk_add_f32 v[36:37], v[36:37], v[32:33]
	ds_read_b128 v[32:35], v30 offset:24576
	s_waitcnt lgkmcnt(0)
	v_pk_add_f32 v[38:39], v[38:39], v[34:35]
	v_pk_add_f32 v[36:37], v[36:37], v[32:33]
	ds_read_b128 v[32:35], v30 offset:32768
	s_waitcnt lgkmcnt(0)
	v_pk_add_f32 v[38:39], v[38:39], v[34:35]
	v_pk_add_f32 v[36:37], v[36:37], v[32:33]
	ds_read_b128 v[32:35], v30 offset:40960
	s_waitcnt lgkmcnt(0)
	v_pk_add_f32 v[38:39], v[38:39], v[34:35]
	v_pk_add_f32 v[36:37], v[36:37], v[32:33]
	ds_read_b128 v[32:35], v30 offset:49152
	s_waitcnt lgkmcnt(0)
	v_pk_add_f32 v[38:39], v[38:39], v[34:35]
	v_pk_add_f32 v[36:37], v[36:37], v[32:33]
	ds_read_b128 v[32:35], v30 offset:57344
	s_waitcnt lgkmcnt(0)
	v_pk_add_f32 v[34:35], v[38:39], v[34:35]
	v_pk_add_f32 v[32:33], v[36:37], v[32:33]
	v_pk_add_f32 v[34:35], v[34:35], v[44:45]
	v_pk_add_f32 v[32:33], v[32:33], v[42:43]
	s_nop 0
	v_cvt_pk_bf16_f32 v36, v32, v33
	v_cvt_pk_bf16_f32 v37, v34, v35
	global_store_dwordx2 v[24:25], v[36:37], off
	v_mul_f32_e32 v0, v33, v33
	v_mul_f32_e32 v24, v35, v35
	v_fmac_f32_e32 v0, v32, v32
	v_fmac_f32_e32 v24, v34, v34
	v_and_b32_e32 v25, 64, v216
	v_add_f32_e32 v0, v0, v24
	v_xor_b32_e32 v24, 1, v216
	v_add_u32_e32 v25, 64, v25
	v_cmp_lt_i32_e32 vcc, v24, v25
	s_nop 1
	v_cndmask_b32_e32 v24, v216, v24, vcc
	v_lshlrev_b32_e32 v24, 2, v24
	ds_bpermute_b32 v24, v24, v0
	s_waitcnt lgkmcnt(0)
	v_add_f32_e32 v0, v0, v24
	v_xor_b32_e32 v24, 2, v216
	v_cmp_lt_i32_e32 vcc, v24, v25
	s_nop 1
	v_cndmask_b32_e32 v24, v216, v24, vcc
	v_lshlrev_b32_e32 v24, 2, v24
	ds_bpermute_b32 v24, v24, v0
	s_waitcnt lgkmcnt(0)
	v_add_f32_e32 v0, v0, v24
	v_xor_b32_e32 v24, 4, v216
	v_cmp_lt_i32_e32 vcc, v24, v25
	s_nop 1
	v_cndmask_b32_e32 v24, v216, v24, vcc
	v_lshlrev_b32_e32 v24, 2, v24
	ds_bpermute_b32 v24, v24, v0
	s_mov_b64 s[0:1], exec
	v_readlane_b32 s10, v255, 23
	v_readlane_b32 s11, v255, 24
	s_and_b64 s[10:11], s[0:1], s[10:11]
	s_mov_b64 exec, s[10:11]
	s_cbranch_execz .LBB0_799
	v_lshl_add_u64 v[22:23], v[22:23], 2, s[4:5]
	s_waitcnt lgkmcnt(0)
	v_add_f32_e32 v0, v0, v24
	global_atomic_add_f32 v[22:23], v0, off
	s_branch .LBB0_799

;     __device__ __forceinline__ void prefetch4(int row, int col, Pre& p) const { p.gw = *(const u32x2*)(Zg + (size_t)row * INC + col); if (SECOND) p.pw = *(const u32x2*)(O + (size_t)row * DM + col); }
; template <int CT, class Epi> __device__ __forceinline__ void skinny_gemm(LAS unsigned char* lds, const bf16_t* A, const bf16_t* Bt, int N, int K, const Epi& E, int first) {
;     ...
;         const bf16_t* ap = A + (size_t)(NTOK_P + mt * 64 + r) * K + wave * kw + 8 * qd;
;         const bf16_t* bp = Bt + (size_t)(nt * 16 * CT + r) * K + wave * kw + 8 * qd;
;         typename Epi::Pre pre[CT / 2];
; #pragma unroll
;         for (int e = 0; e < CT / 2; ++e) { const int idx = tid + e * 512; E.prefetch4(NTOK_P + mt * 64 + idx / (4 * CT), nt * 16 * CT + (idx % (4 * CT)) * 4, pre[e]); }
;         f32x4 acc[4][CT];
; #pragma unroll
;         for (int rt = 0; rt < 4; ++rt)
; #pragma unroll
;             for (int ct = 0; ct < CT; ++ct) acc[rt][ct] = (f32x4){0.f, 0.f, 0.f, 0.f};
.LBB0_876:
	s_and_b32 s7, s0, 0x1c0
	s_or_b32 s8, s7, 0x4000
	v_or_b32_e32 v0, s8, v24
	v_lshlrev_b32_e32 v0, 11, v0
	v_lshl_add_u64 v[112:113], v[2:3], 0, v[0:1]
	v_add_co_u32_e32 v140, vcc, s85, v112
	s_and_b32 s7, s1, 0xffffffc0
	s_nop 0
	v_addc_co_u32_e32 v141, vcc, 0, v113, vcc
	v_or_b32_e32 v22, s7, v24
	v_add_co_u32_e32 v128, vcc, s73, v112
	v_ashrrev_i32_e32 v23, 31, v22
	s_nop 0
	v_addc_co_u32_e32 v129, vcc, 0, v113, vcc
	v_lshlrev_b64 v[40:41], 11, v[22:23]
	v_add_co_u32_e32 v136, vcc, s35, v112
	v_lshl_add_u64 v[144:145], v[20:21], 0, v[40:41]
	s_nop 0
	v_addc_co_u32_e32 v137, vcc, 0, v113, vcc
	v_add_co_u32_e32 v152, vcc, s85, v144
	v_add_u32_e32 v186, s8, v28
	s_nop 0
	v_addc_co_u32_e32 v153, vcc, 0, v145, vcc
	v_add_co_u32_e32 v160, vcc, s73, v144
	v_add_u32_e32 v22, s8, v25
	s_nop 0
	v_addc_co_u32_e32 v161, vcc, 0, v145, vcc
	v_ashrrev_i32_e32 v187, 31, v186
	v_ashrrev_i32_e32 v23, 31, v22
	v_add_co_u32_e32 v164, vcc, s35, v144
	v_lshl_add_u64 v[42:43], v[186:187], 2, s[4:5]
	v_lshl_add_u64 v[44:45], v[22:23], 2, s[4:5]
	v_addc_co_u32_e32 v165, vcc, 0, v145, vcc
	global_load_dword v0, v[42:43], off
	global_load_dword v188, v[44:45], off
	s_nop 0
	s_mov_b32 s100, 0x4000
	s_mov_b32 s101, 0
	v_readfirstlane_b32 s98, v184
	v_and_b32_e32 v246, 63, v184
	s_nop 1
	s_lshr_b32 s98, s98, 6
	s_lshl_b32 s98, s98, 14
	v_and_b32_e32 v247, 15, v246
	v_lshrrev_b32_e32 v248, 4, v246
	v_lshrrev_b32_e32 v249, 3, v246
	v_and_b32_e32 v246, 7, v246
	v_xor_b32_e32 v246, v246, v249
	v_sub_u32_e32 v249, v249, v247
	v_sub_u32_e32 v246, v246, v248
	v_lshlrev_b32_e32 v249, 11, v249
	v_lshl_add_u32 v240, v246, 4, v249
	v_ashrrev_i32_e32 v241, 31, v240
	v_and_b32_e32 v246, 7, v247
	v_xor_b32_e32 v246, v246, v248
	v_lshlrev_b32_e32 v246, 4, v246
	v_lshl_add_u32 v246, v247, 7, v246
	v_add_u32_e32 v242, s98, v246
	v_xor_b32_e32 v243, 64, v242
	v_add_u32_e32 v246, 0x80, v240
	v_ashrrev_i32_e32 v247, 31, v246
	s_mov_b32 m0, s98
	v_lshl_add_u64 v[236:237], v[112:113], 0, v[240:241]
	global_load_lds_dwordx4 v[236:237], off
	s_add_i32 m0, s98, 0x400
	v_lshl_add_u64 v[236:237], v[236:237], 0, s[100:101]
	global_load_lds_dwordx4 v[236:237], off
	s_add_i32 m0, s98, 0x800
	v_lshl_add_u64 v[236:237], v[236:237], 0, s[100:101]
	global_load_lds_dwordx4 v[236:237], off
	s_add_i32 m0, s98, 0xc00
	v_lshl_add_u64 v[236:237], v[236:237], 0, s[100:101]
	global_load_lds_dwordx4 v[236:237], off
	s_add_i32 m0, s98, 0x1000
	v_lshl_add_u64 v[236:237], v[236:237], 0, s[100:101]
	global_load_lds_dwordx4 v[236:237], off
	s_add_i32 m0, s98, 0x1400
	v_lshl_add_u64 v[236:237], v[236:237], 0, s[100:101]
	global_load_lds_dwordx4 v[236:237], off
	s_add_i32 m0, s98, 0x1800
	v_lshl_add_u64 v[236:237], v[236:237], 0, s[100:101]
	global_load_lds_dwordx4 v[236:237], off
	s_add_i32 m0, s98, 0x1c00
	v_lshl_add_u64 v[236:237], v[236:237], 0, s[100:101]
	global_load_lds_dwordx4 v[236:237], off
	s_add_i32 m0, s98, 0x2000
	v_lshl_add_u64 v[238:239], v[144:145], 0, v[240:241]
	global_load_lds_dwordx4 v[238:239], off
	s_add_i32 m0, s98, 0x2400
	v_lshl_add_u64 v[238:239], v[238:239], 0, s[100:101]
	global_load_lds_dwordx4 v[238:239], off
	s_add_i32 m0, s98, 0x2800
	v_lshl_add_u64 v[238:239], v[238:239], 0, s[100:101]
	global_load_lds_dwordx4 v[238:239], off
	s_add_i32 m0, s98, 0x2c00
	v_lshl_add_u64 v[238:239], v[238:239], 0, s[100:101]
	global_load_lds_dwordx4 v[238:239], off
	s_add_i32 m0, s98, 0x3000
	v_lshl_add_u64 v[238:239], v[238:239], 0, s[100:101]
	global_load_lds_dwordx4 v[238:239], off
	s_add_i32 m0, s98, 0x3400
	v_lshl_add_u64 v[238:239], v[238:239], 0, s[100:101]
	global_load_lds_dwordx4 v[238:239], off
	s_add_i32 m0, s98, 0x3800
	v_lshl_add_u64 v[238:239], v[238:239], 0, s[100:101]
	global_load_lds_dwordx4 v[238:239], off
	s_add_i32 m0, s98, 0x3c00
	v_lshl_add_u64 v[238:239], v[238:239], 0, s[100:101]
	global_load_lds_dwordx4 v[238:239], off
	s_waitcnt vmcnt(0)
	ds_read_b128 v[40:43], v242
	ds_read_b128 v[140:143], v242 offset:2048
	ds_read_b128 v[116:119], v242 offset:4096
	ds_read_b128 v[124:127], v242 offset:6144
	ds_read_b128 v[44:47], v243
	ds_read_b128 v[52:55], v243 offset:2048
	ds_read_b128 v[60:63], v243 offset:4096
	ds_read_b128 v[68:71], v243 offset:6144
	ds_read_b128 v[108:111], v242 offset:8192
	ds_read_b128 v[132:135], v242 offset:10240
	ds_read_b128 v[148:151], v242 offset:12288
	ds_read_b128 v[156:159], v242 offset:14336
	ds_read_b128 v[76:79], v243 offset:8192
	ds_read_b128 v[84:87], v243 offset:10240
	ds_read_b128 v[92:95], v243 offset:12288
	ds_read_b128 v[100:103], v243 offset:14336
	s_waitcnt lgkmcnt(0)
	s_mov_b32 m0, s98
	v_lshl_add_u64 v[236:237], v[112:113], 0, v[246:247]
	global_load_lds_dwordx4 v[236:237], off
	s_add_i32 m0, s98, 0x400
	v_lshl_add_u64 v[236:237], v[236:237], 0, s[100:101]
	global_load_lds_dwordx4 v[236:237], off
	s_add_i32 m0, s98, 0x800
	v_lshl_add_u64 v[236:237], v[236:237], 0, s[100:101]
	global_load_lds_dwordx4 v[236:237], off
	s_add_i32 m0, s98, 0xc00
	v_lshl_add_u64 v[236:237], v[236:237], 0, s[100:101]
	global_load_lds_dwordx4 v[236:237], off
	s_add_i32 m0, s98, 0x1000
	v_lshl_add_u64 v[236:237], v[236:237], 0, s[100:101]
	global_load_lds_dwordx4 v[236:237], off
	s_add_i32 m0, s98, 0x1400
	v_lshl_add_u64 v[236:237], v[236:237], 0, s[100:101]
	global_load_lds_dwordx4 v[236:237], off
	s_add_i32 m0, s98, 0x1800
	v_lshl_add_u64 v[236:237], v[236:237], 0, s[100:101]
	global_load_lds_dwordx4 v[236:237], off
	s_add_i32 m0, s98, 0x1c00
	v_lshl_add_u64 v[236:237], v[236:237], 0, s[100:101]
	global_load_lds_dwordx4 v[236:237], off
	s_add_i32 m0, s98, 0x2000
	v_lshl_add_u64 v[238:239], v[144:145], 0, v[246:247]
	global_load_lds_dwordx4 v[238:239], off
	s_add_i32 m0, s98, 0x2400
	v_lshl_add_u64 v[238:239], v[238:239], 0, s[100:101]
	global_load_lds_dwordx4 v[238:239], off
	s_add_i32 m0, s98, 0x2800
	v_lshl_add_u64 v[238:239], v[238:239], 0, s[100:101]
	global_load_lds_dwordx4 v[238:239], off
	s_add_i32 m0, s98, 0x2c00
	v_lshl_add_u64 v[238:239], v[238:239], 0, s[100:101]
	global_load_lds_dwordx4 v[238:239], off
	s_add_i32 m0, s98, 0x3000
	v_lshl_add_u64 v[238:239], v[238:239], 0, s[100:101]
	global_load_lds_dwordx4 v[238:239], off
	s_add_i32 m0, s98, 0x3400
	v_lshl_add_u64 v[238:239], v[238:239], 0, s[100:101]
	global_load_lds_dwordx4 v[238:239], off
	s_add_i32 m0, s98, 0x3800
	v_lshl_add_u64 v[238:239], v[238:239], 0, s[100:101]
	global_load_lds_dwordx4 v[238:239], off
	s_add_i32 m0, s98, 0x3c00
	v_lshl_add_u64 v[238:239], v[238:239], 0, s[100:101]
	global_load_lds_dwordx4 v[238:239], off
	s_nop 0
	s_nop 0
	s_nop 0
	s_nop 0
	s_nop 0
	s_nop 0
	s_nop 0
	s_nop 0
	s_nop 0
	s_nop 0
	s_nop 0
	s_nop 0
	v_mfma_f32_16x16x32_bf16 v[168:171], v[108:111], v[40:43], 0
	v_mfma_f32_16x16x32_bf16 v[172:175], v[132:135], v[40:43], 0
	v_mfma_f32_16x16x32_bf16 v[176:179], v[148:151], v[40:43], 0
	v_mfma_f32_16x16x32_bf16 v[40:43], v[156:159], v[40:43], 0
	v_mfma_f32_16x16x32_bf16 v[180:183], v[108:111], v[140:143], 0
	v_mfma_f32_16x16x32_bf16 v[190:193], v[132:135], v[140:143], 0
	v_mfma_f32_16x16x32_bf16 v[194:197], v[148:151], v[140:143], 0
	v_mfma_f32_16x16x32_bf16 v[140:143], v[156:159], v[140:143], 0
	v_mfma_f32_16x16x32_bf16 v[198:201], v[108:111], v[116:119], 0
	v_mfma_f32_16x16x32_bf16 v[202:205], v[132:135], v[116:119], 0
	v_mfma_f32_16x16x32_bf16 v[206:209], v[148:151], v[116:119], 0
	v_mfma_f32_16x16x32_bf16 v[116:119], v[156:159], v[116:119], 0
	v_mfma_f32_16x16x32_bf16 v[108:111], v[108:111], v[124:127], 0
	v_mfma_f32_16x16x32_bf16 v[132:135], v[132:135], v[124:127], 0
	v_mfma_f32_16x16x32_bf16 v[148:151], v[148:151], v[124:127], 0
	v_mfma_f32_16x16x32_bf16 v[124:127], v[156:159], v[124:127], 0
	v_mfma_f32_16x16x32_bf16 v[156:159], v[76:79], v[44:47], v[168:171]
	v_mfma_f32_16x16x32_bf16 v[168:171], v[84:87], v[44:47], v[172:175]
	v_mfma_f32_16x16x32_bf16 v[172:175], v[92:95], v[44:47], v[176:179]
	v_mfma_f32_16x16x32_bf16 v[40:43], v[100:103], v[44:47], v[40:43]
	v_mfma_f32_16x16x32_bf16 v[44:47], v[76:79], v[52:55], v[180:183]
	v_mfma_f32_16x16x32_bf16 v[176:179], v[84:87], v[52:55], v[190:193]
	v_mfma_f32_16x16x32_bf16 v[180:183], v[92:95], v[52:55], v[194:197]
	v_mfma_f32_16x16x32_bf16 v[52:55], v[100:103], v[52:55], v[140:143]
	v_mfma_f32_16x16x32_bf16 v[140:143], v[76:79], v[60:63], v[198:201]
	v_mfma_f32_16x16x32_bf16 v[190:193], v[84:87], v[60:63], v[202:205]
	v_mfma_f32_16x16x32_bf16 v[194:197], v[92:95], v[60:63], v[206:209]
	v_mfma_f32_16x16x32_bf16 v[60:63], v[100:103], v[60:63], v[116:119]
	v_mfma_f32_16x16x32_bf16 v[76:79], v[76:79], v[68:71], v[108:111]
	v_mfma_f32_16x16x32_bf16 v[84:87], v[84:87], v[68:71], v[132:135]
	v_mfma_f32_16x16x32_bf16 v[92:95], v[92:95], v[68:71], v[148:151]
	v_mfma_f32_16x16x32_bf16 v[68:71], v[100:103], v[68:71], v[124:127]
	s_waitcnt vmcnt(0)
	ds_read_b128 v[48:51], v242
	ds_read_b128 v[56:59], v242 offset:2048
	ds_read_b128 v[64:67], v242 offset:4096
	ds_read_b128 v[72:75], v242 offset:6144
	ds_read_b128 v[112:115], v243
	ds_read_b128 v[120:123], v243 offset:2048
	ds_read_b128 v[128:131], v243 offset:4096
	ds_read_b128 v[136:139], v243 offset:6144
	ds_read_b128 v[80:83], v242 offset:8192
	ds_read_b128 v[88:91], v242 offset:10240
	ds_read_b128 v[96:99], v242 offset:12288
	ds_read_b128 v[104:107], v242 offset:14336
	ds_read_b128 v[144:147], v243 offset:8192
	ds_read_b128 v[152:155], v243 offset:10240
	ds_read_b128 v[160:163], v243 offset:12288
	ds_read_b128 v[164:167], v243 offset:14336
	s_waitcnt lgkmcnt(0)
; #define LAS __attribute__((address_space(3)))
; __device__ __forceinline__ unsigned pk2(float lo, float hi) { return pg8::cvt_pk_bf16(lo, hi); }
;     __device__ __forceinline__ void apply4(int row, int col, f32x4 v, const Pre& p) const {
;         const float rs = rsqrtf(p.ssv * (1.f / DM) + EPS);
; #pragma unroll
;         for (int k = 0; k < 4; ++k) { const float t = fmaxf(v[k] * rs, 0.f); v[k] = t * t; }
;         u32x2 w; w.x = pk2(v[0], v[1]); w.y = pk2(v[2], v[3]); *(u32x2*)(H + (size_t)row * FF + col) = w;
; template <int CT, class Epi> __device__ __forceinline__ void skinny_gemm(LAS unsigned char* lds, const bf16_t* A, const bf16_t* Bt, int N, int K, const Epi& E, int first) {
;     ...
;         if (nsteps >= 4) {
; #pragma unroll 1
;             for (int s0 = 0; s0 < nsteps; s0 += 4) SKINNY_GROUP(4, s0);
;         } else SKINNY_GROUP(2, 0);
;     ...
; #pragma unroll
;         for (int rt = 0; rt < 4; ++rt)
; #pragma unroll
;             for (int ct = 0; ct < CT; ++ct) *(LAS f32x4*)(red + wave * (64 * 16 * CT) + (rt * 16 + r) * (16 * CT) + ct * 16 + 4 * qd) = acc[rt][ct];
;         __syncthreads();
; #pragma unroll
;         for (int e = 0; e < CT / 2; ++e) { const int idx = tid + e * 512, row = idx / (4 * CT), c4 = idx % (4 * CT);
;             f32x4 v = *(const LAS f32x4*)(red + row * (16 * CT) + c4 * 4);
; #pragma unroll
;             for (int w = 1; w < 8; ++w) v = v + *(const LAS f32x4*)(red + w * (64 * 16 * CT) + row * (16 * CT) + c4 * 4);
;             E.apply4(NTOK_P + mt * 64 + row, nt * 16 * CT + c4 * 4, v, pre[e]); }
	v_mfma_f32_16x16x32_bf16 v[100:103], v[80:83], v[48:51], v[156:159]
	v_mfma_f32_16x16x32_bf16 v[108:111], v[88:91], v[48:51], v[168:171]
	v_mfma_f32_16x16x32_bf16 v[116:119], v[96:99], v[48:51], v[172:175]
	v_mfma_f32_16x16x32_bf16 v[40:43], v[104:107], v[48:51], v[40:43]
	v_mfma_f32_16x16x32_bf16 v[44:47], v[80:83], v[56:59], v[44:47]
	v_mfma_f32_16x16x32_bf16 v[48:51], v[88:91], v[56:59], v[176:179]
	v_mfma_f32_16x16x32_bf16 v[124:127], v[96:99], v[56:59], v[180:183]
	v_mfma_f32_16x16x32_bf16 v[52:55], v[104:107], v[56:59], v[52:55]
	v_mfma_f32_16x16x32_bf16 v[56:59], v[80:83], v[64:67], v[140:143]
	v_mfma_f32_16x16x32_bf16 v[132:135], v[88:91], v[64:67], v[190:193]
	v_mfma_f32_16x16x32_bf16 v[140:143], v[96:99], v[64:67], v[194:197]
	v_mfma_f32_16x16x32_bf16 v[60:63], v[104:107], v[64:67], v[60:63]
	v_mfma_f32_16x16x32_bf16 v[64:67], v[80:83], v[72:75], v[76:79]
	v_mfma_f32_16x16x32_bf16 v[76:79], v[88:91], v[72:75], v[84:87]
	v_mfma_f32_16x16x32_bf16 v[80:83], v[96:99], v[72:75], v[92:95]
	v_mfma_f32_16x16x32_bf16 v[68:71], v[104:107], v[72:75], v[68:71]
	v_mfma_f32_16x16x32_bf16 v[72:75], v[144:147], v[112:115], v[100:103]
	v_mfma_f32_16x16x32_bf16 v[84:87], v[152:155], v[112:115], v[108:111]
	v_mfma_f32_16x16x32_bf16 v[88:91], v[160:163], v[112:115], v[116:119]
	v_mfma_f32_16x16x32_bf16 v[40:43], v[164:167], v[112:115], v[40:43]
	v_mfma_f32_16x16x32_bf16 v[44:47], v[144:147], v[120:123], v[44:47]
	v_mfma_f32_16x16x32_bf16 v[48:51], v[152:155], v[120:123], v[48:51]
	v_mfma_f32_16x16x32_bf16 v[92:95], v[160:163], v[120:123], v[124:127]
	v_mfma_f32_16x16x32_bf16 v[52:55], v[164:167], v[120:123], v[52:55]
	v_mfma_f32_16x16x32_bf16 v[56:59], v[144:147], v[128:131], v[56:59]
	v_mfma_f32_16x16x32_bf16 v[96:99], v[152:155], v[128:131], v[132:135]
	v_mfma_f32_16x16x32_bf16 v[100:103], v[160:163], v[128:131], v[140:143]
	v_mfma_f32_16x16x32_bf16 v[60:63], v[164:167], v[128:131], v[60:63]
	v_mfma_f32_16x16x32_bf16 v[64:67], v[144:147], v[136:139], v[64:67]
	v_mfma_f32_16x16x32_bf16 v[76:79], v[152:155], v[136:139], v[76:79]
	v_mfma_f32_16x16x32_bf16 v[80:83], v[160:163], v[136:139], v[80:83]
	v_mfma_f32_16x16x32_bf16 v[68:71], v[164:167], v[136:139], v[68:71]
	ds_write_b128 v39, v[72:75]
	ds_write_b128 v39, v[84:87] offset:64
	ds_write_b128 v39, v[88:91] offset:128
	ds_write_b128 v39, v[40:43] offset:192
	ds_write_b128 v39, v[44:47] offset:4096
	ds_write_b128 v39, v[48:51] offset:4160
	ds_write_b128 v39, v[92:95] offset:4224
	ds_write_b128 v39, v[52:55] offset:4288
	ds_write_b128 v39, v[56:59] offset:8192
	ds_write_b128 v39, v[96:99] offset:8256
	ds_write_b128 v39, v[100:103] offset:8320
	ds_write_b128 v39, v[60:63] offset:8384
	ds_write_b128 v39, v[64:67] offset:12288
	ds_write_b128 v39, v[76:79] offset:12352
	ds_write_b128 v39, v[80:83] offset:12416
	ds_write_b128 v39, v[68:71] offset:12480
	s_waitcnt lgkmcnt(0)
	s_barrier
	ds_read_b128 v[40:43], v30
	ds_read_b128 v[44:47], v30 offset:16384
	ds_read_b128 v[48:51], v30 offset:32768
	ds_read_b128 v[52:55], v30 offset:49152
	v_fmamk_f32 v0, v0, 0x3a800000, v185
	v_cmp_gt_f32_e32 vcc, s86, v0
	s_waitcnt lgkmcnt(2)
	v_pk_add_f32 v[42:43], v[42:43], v[46:47]
	v_pk_add_f32 v[44:45], v[40:41], v[44:45]
	s_waitcnt lgkmcnt(1)
	v_pk_add_f32 v[46:47], v[42:43], v[50:51]
	ds_read_b128 v[40:43], v31
	v_pk_add_f32 v[48:49], v[44:45], v[48:49]
	s_waitcnt lgkmcnt(1)
	v_pk_add_f32 v[50:51], v[46:47], v[54:55]
	ds_read_b128 v[44:47], v32
	v_pk_add_f32 v[52:53], v[48:49], v[52:53]
	s_waitcnt lgkmcnt(1)
	v_pk_add_f32 v[42:43], v[50:51], v[42:43]
	ds_read_b128 v[48:51], v33
	v_pk_add_f32 v[40:41], v[52:53], v[40:41]
	s_waitcnt lgkmcnt(1)
	v_pk_add_f32 v[46:47], v[42:43], v[46:47]
	v_pk_add_f32 v[44:45], v[40:41], v[44:45]
	ds_read_b128 v[40:43], v34
	s_waitcnt lgkmcnt(1)
	v_pk_add_f32 v[44:45], v[44:45], v[48:49]
	v_mul_f32_e32 v48, 0x4b800000, v0
	v_cndmask_b32_e32 v0, v0, v48, vcc
	v_rsq_f32_e32 v0, v0
	s_waitcnt lgkmcnt(0)
	v_pk_add_f32 v[40:41], v[44:45], v[40:41]
	v_pk_add_f32 v[46:47], v[46:47], v[50:51]
	v_add_u32_e32 v48, s7, v29
	v_mul_f32_e32 v44, 0x45800000, v0
	v_cndmask_b32_e32 v0, v0, v44, vcc
	v_pk_add_f32 v[42:43], v[46:47], v[42:43]
	v_mul_f32_e32 v40, v0, v40
	v_mul_f32_e32 v41, v0, v41
	v_max_f32_e32 v40, 0, v40
	v_max_f32_e32 v41, 0, v41
	v_mul_f32_e32 v42, v0, v42
	v_mul_f32_e32 v40, v40, v40
	v_mul_f32_e32 v41, v41, v41
	v_max_f32_e32 v42, 0, v42
	v_mul_f32_e32 v0, v0, v43
	v_mul_f32_e32 v42, v42, v42
	v_max_f32_e32 v0, 0, v0
	v_cvt_pk_bf16_f32 v52, v40, v41
	v_lshlrev_b64 v[40:41], 13, v[186:187]
	v_mul_f32_e32 v0, v0, v0
	v_cvt_pk_bf16_f32 v53, v42, v0
	v_lshl_add_u64 v[50:51], s[48:49], 0, v[40:41]
	ds_read_b128 v[40:43], v27
	ds_read_b128 v[44:47], v27 offset:16384
	v_ashrrev_i32_e32 v49, 31, v48
	v_lshl_add_u64 v[54:55], v[48:49], 1, v[50:51]
	ds_read_b128 v[48:51], v27 offset:32768
	global_store_dwordx2 v[54:55], v[52:53], off
	s_waitcnt lgkmcnt(1)
	v_pk_add_f32 v[42:43], v[42:43], v[46:47]
	ds_read_b128 v[52:55], v27 offset:49152
	v_pk_add_f32 v[44:45], v[40:41], v[44:45]
	s_waitcnt lgkmcnt(1)
	v_pk_add_f32 v[46:47], v[42:43], v[50:51]
	ds_read_b128 v[40:43], v35
	v_pk_add_f32 v[48:49], v[44:45], v[48:49]
	s_waitcnt lgkmcnt(1)
	v_pk_add_f32 v[50:51], v[46:47], v[54:55]
	ds_read_b128 v[44:47], v36
	v_pk_add_f32 v[52:53], v[48:49], v[52:53]
	s_waitcnt lgkmcnt(1)
	v_pk_add_f32 v[42:43], v[50:51], v[42:43]
	ds_read_b128 v[48:51], v37
	v_pk_add_f32 v[40:41], v[52:53], v[40:41]
	v_fmamk_f32 v0, v188, 0x3a800000, v185
	s_waitcnt lgkmcnt(1)
	v_pk_add_f32 v[44:45], v[40:41], v[44:45]
	v_pk_add_f32 v[46:47], v[42:43], v[46:47]
	ds_read_b128 v[40:43], v38
	s_waitcnt lgkmcnt(1)
	v_pk_add_f32 v[44:45], v[44:45], v[48:49]
	v_mul_f32_e32 v48, 0x4b800000, v0
	v_cmp_gt_f32_e32 vcc, s86, v0
	v_pk_add_f32 v[46:47], v[46:47], v[50:51]
	s_waitcnt lgkmcnt(0)
	v_pk_add_f32 v[40:41], v[44:45], v[40:41]
	v_cndmask_b32_e32 v0, v0, v48, vcc
	v_rsq_f32_e32 v0, v0
	v_pk_add_f32 v[42:43], v[46:47], v[42:43]
	v_add_u32_e32 v44, s7, v26
	v_lshlrev_b64 v[22:23], 13, v[22:23]
	v_mul_f32_e32 v45, 0x45800000, v0
	v_cndmask_b32_e32 v0, v0, v45, vcc
	v_mul_f32_e32 v40, v0, v40
	v_mul_f32_e32 v41, v0, v41
	v_max_f32_e32 v40, 0, v40
	v_max_f32_e32 v41, 0, v41
	v_mul_f32_e32 v42, v0, v42
	v_mul_f32_e32 v0, v0, v43
	v_lshl_add_u64 v[22:23], s[48:49], 0, v[22:23]
	v_ashrrev_i32_e32 v45, 31, v44
	s_add_i32 s6, s6, s34
	s_add_i32 s1, s1, s10
	s_add_i32 s0, s0, s82
	v_mul_f32_e32 v40, v40, v40
	v_mul_f32_e32 v41, v41, v41
	v_max_f32_e32 v42, 0, v42
	v_max_f32_e32 v0, 0, v0
	v_lshl_add_u64 v[22:23], v[44:45], 1, v[22:23]
	s_cmpk_lt_i32 s6, 0x200
	v_mul_f32_e32 v42, v42, v42
	v_mul_f32_e32 v0, v0, v0
	v_cvt_pk_bf16_f32 v40, v40, v41
	v_cvt_pk_bf16_f32 v41, v42, v0
	global_store_dwordx2 v[22:23], v[40:41], off
	s_barrier
	s_cbranch_scc1 .LBB0_876

; template <int CT, class Epi> __device__ __forceinline__ void skinny_gemm(LAS unsigned char* lds, const bf16_t* A, const bf16_t* Bt, int N, int K, const Epi& E, int first) {
;     ...
;         if (nsteps >= 4) {
; #pragma unroll 1
;             for (int s0 = 0; s0 < nsteps; s0 += 4) SKINNY_GROUP(4, s0);
.LBB0_1034:
	s_waitcnt vmcnt(3)
	v_lshl_add_u64 v[68:69], v[58:59], 0, v[0:1]
	s_mov_b32 s5, 0x7b00000
	v_add_co_u32_e32 v120, vcc, s5, v68
	s_mov_b32 s5, 0x7b20000
	s_nop 0
	v_addc_co_u32_e32 v121, vcc, 0, v69, vcc
	v_add_co_u32_e32 v128, vcc, s5, v68
	s_mov_b32 s5, 0x7b40000
	s_nop 0
	v_addc_co_u32_e32 v129, vcc, 0, v69, vcc
	v_add_co_u32_e32 v136, vcc, s5, v68
	s_mov_b32 s5, 0x7b60000
	s_nop 0
	v_addc_co_u32_e32 v137, vcc, 0, v69, vcc
	v_add_co_u32_e32 v144, vcc, s5, v68
	s_mov_b32 s5, 0x1600000
	s_nop 0
	v_addc_co_u32_e32 v145, vcc, 0, v69, vcc
	v_lshl_add_u64 v[68:69], v[58:59], 0, v[56:57]
	v_add_co_u32_e32 v152, vcc, s5, v68
	s_mov_b32 s5, 0x1620000
	s_nop 0
	v_addc_co_u32_e32 v153, vcc, 0, v69, vcc
	v_add_co_u32_e32 v160, vcc, s5, v68
	s_nop 1
	v_addc_co_u32_e32 v161, vcc, 0, v69, vcc
	s_mov_b32 s100, 0x10000
	s_mov_b32 s101, 0
	v_readfirstlane_b32 s98, v184
	v_and_b32_e32 v246, 63, v184
	s_nop 1
	s_lshr_b32 s98, s98, 6
	s_lshl_b32 s99, s98, 12
	s_add_i32 s99, s99, 0x10000
	s_lshl_b32 s98, s98, 13
	v_and_b32_e32 v247, 15, v246
	v_lshrrev_b32_e32 v248, 4, v246
	v_lshrrev_b32_e32 v249, 3, v246
	v_and_b32_e32 v246, 7, v246
	v_xor_b32_e32 v246, v246, v249
	v_sub_u32_e32 v249, v249, v247
	v_sub_u32_e32 v246, v246, v248
	v_lshlrev_b32_e32 v249, 13, v249
	v_lshl_add_u32 v240, v246, 4, v249
	v_ashrrev_i32_e32 v241, 31, v240
	v_and_b32_e32 v246, 7, v247
	v_xor_b32_e32 v246, v246, v248
	v_lshlrev_b32_e32 v246, 4, v246
	v_lshl_add_u32 v246, v247, 7, v246
	v_add_u32_e32 v242, s98, v246
	v_xor_b32_e32 v243, 64, v242
	v_add_u32_e32 v244, s99, v246
	v_xor_b32_e32 v245, 64, v244
	v_add_u32_e32 v246, 0x80, v240
	v_ashrrev_i32_e32 v247, 31, v246
	s_mov_b32 m0, s98
	v_lshl_add_u64 v[236:237], v[120:121], 0, v[240:241]
	global_load_lds_dwordx4 v[236:237], off
	s_add_i32 m0, s98, 0x400
	v_lshl_add_u64 v[236:237], v[236:237], 0, s[100:101]
	global_load_lds_dwordx4 v[236:237], off
	s_add_i32 m0, s98, 0x800
	v_lshl_add_u64 v[236:237], v[236:237], 0, s[100:101]
	global_load_lds_dwordx4 v[236:237], off
	s_add_i32 m0, s98, 0xc00
	v_lshl_add_u64 v[236:237], v[236:237], 0, s[100:101]
	global_load_lds_dwordx4 v[236:237], off
	s_add_i32 m0, s98, 0x1000
	v_lshl_add_u64 v[236:237], v[236:237], 0, s[100:101]
	global_load_lds_dwordx4 v[236:237], off
	s_add_i32 m0, s98, 0x1400
	v_lshl_add_u64 v[236:237], v[236:237], 0, s[100:101]
	global_load_lds_dwordx4 v[236:237], off
	s_add_i32 m0, s98, 0x1800
	v_lshl_add_u64 v[236:237], v[236:237], 0, s[100:101]
	global_load_lds_dwordx4 v[236:237], off
	s_add_i32 m0, s98, 0x1c00
	v_lshl_add_u64 v[236:237], v[236:237], 0, s[100:101]
	global_load_lds_dwordx4 v[236:237], off
	s_mov_b32 m0, s99
	v_lshl_add_u64 v[238:239], v[152:153], 0, v[240:241]
	global_load_lds_dwordx4 v[238:239], off
	s_add_i32 m0, s99, 0x400
	v_lshl_add_u64 v[238:239], v[238:239], 0, s[100:101]
	global_load_lds_dwordx4 v[238:239], off
	s_add_i32 m0, s99, 0x800
	v_lshl_add_u64 v[238:239], v[238:239], 0, s[100:101]
	global_load_lds_dwordx4 v[238:239], off
	s_add_i32 m0, s99, 0xc00
	v_lshl_add_u64 v[238:239], v[238:239], 0, s[100:101]
	global_load_lds_dwordx4 v[238:239], off
	s_waitcnt vmcnt(0)
	ds_read_b128 v[68:71], v242
	ds_read_b128 v[76:79], v242 offset:2048
	ds_read_b128 v[84:87], v242 offset:4096
	ds_read_b128 v[92:95], v242 offset:6144
	ds_read_b128 v[72:75], v243
	ds_read_b128 v[80:83], v243 offset:2048
	ds_read_b128 v[88:91], v243 offset:4096
	ds_read_b128 v[96:99], v243 offset:6144
	ds_read_b128 v[100:103], v244
	ds_read_b128 v[108:111], v244 offset:2048
	ds_read_b128 v[104:107], v245
	ds_read_b128 v[112:115], v245 offset:2048
	s_waitcnt lgkmcnt(0)
	s_mov_b32 m0, s98
	v_lshl_add_u64 v[236:237], v[120:121], 0, v[246:247]
	global_load_lds_dwordx4 v[236:237], off
	s_add_i32 m0, s98, 0x400
	v_lshl_add_u64 v[236:237], v[236:237], 0, s[100:101]
	global_load_lds_dwordx4 v[236:237], off
	s_add_i32 m0, s98, 0x800
	v_lshl_add_u64 v[236:237], v[236:237], 0, s[100:101]
	global_load_lds_dwordx4 v[236:237], off
	s_add_i32 m0, s98, 0xc00
	v_lshl_add_u64 v[236:237], v[236:237], 0, s[100:101]
	global_load_lds_dwordx4 v[236:237], off
	s_add_i32 m0, s98, 0x1000
	v_lshl_add_u64 v[236:237], v[236:237], 0, s[100:101]
	global_load_lds_dwordx4 v[236:237], off
	s_add_i32 m0, s98, 0x1400
	v_lshl_add_u64 v[236:237], v[236:237], 0, s[100:101]
	global_load_lds_dwordx4 v[236:237], off
	s_add_i32 m0, s98, 0x1800
	v_lshl_add_u64 v[236:237], v[236:237], 0, s[100:101]
	global_load_lds_dwordx4 v[236:237], off
	s_add_i32 m0, s98, 0x1c00
	v_lshl_add_u64 v[236:237], v[236:237], 0, s[100:101]
	global_load_lds_dwordx4 v[236:237], off
	s_mov_b32 m0, s99
	v_lshl_add_u64 v[238:239], v[152:153], 0, v[246:247]
	global_load_lds_dwordx4 v[238:239], off
	s_add_i32 m0, s99, 0x400
	v_lshl_add_u64 v[238:239], v[238:239], 0, s[100:101]
	global_load_lds_dwordx4 v[238:239], off
	s_add_i32 m0, s99, 0x800
	v_lshl_add_u64 v[238:239], v[238:239], 0, s[100:101]
	global_load_lds_dwordx4 v[238:239], off
	s_add_i32 m0, s99, 0xc00
	v_lshl_add_u64 v[238:239], v[238:239], 0, s[100:101]
	global_load_lds_dwordx4 v[238:239], off
	s_nop 0
	s_nop 0
	s_nop 0
	s_nop 0
	s_nop 0
	s_nop 0
	s_nop 0
	s_nop 0
	s_nop 0
	s_nop 0
	s_nop 0
	v_mfma_f32_16x16x32_bf16 v[20:23], v[100:103], v[68:71], v[20:23]
	v_mfma_f32_16x16x32_bf16 v[24:27], v[108:111], v[68:71], v[24:27]
	v_mfma_f32_16x16x32_bf16 v[28:31], v[100:103], v[76:79], v[28:31]
	v_mfma_f32_16x16x32_bf16 v[32:35], v[108:111], v[76:79], v[32:35]
	v_mfma_f32_16x16x32_bf16 v[36:39], v[100:103], v[84:87], v[36:39]
	v_mfma_f32_16x16x32_bf16 v[40:43], v[108:111], v[84:87], v[40:43]
	v_mfma_f32_16x16x32_bf16 v[44:47], v[100:103], v[92:95], v[44:47]
	v_mfma_f32_16x16x32_bf16 v[48:51], v[108:111], v[92:95], v[48:51]
	v_mfma_f32_16x16x32_bf16 v[20:23], v[104:107], v[72:75], v[20:23]
	v_mfma_f32_16x16x32_bf16 v[24:27], v[112:115], v[72:75], v[24:27]
	v_mfma_f32_16x16x32_bf16 v[28:31], v[104:107], v[80:83], v[28:31]
	v_mfma_f32_16x16x32_bf16 v[32:35], v[112:115], v[80:83], v[32:35]
	v_mfma_f32_16x16x32_bf16 v[36:39], v[104:107], v[88:91], v[36:39]
	v_mfma_f32_16x16x32_bf16 v[40:43], v[112:115], v[88:91], v[40:43]
	v_mfma_f32_16x16x32_bf16 v[44:47], v[104:107], v[96:99], v[44:47]
	v_mfma_f32_16x16x32_bf16 v[48:51], v[112:115], v[96:99], v[48:51]
	s_waitcnt vmcnt(0)
; #define LAS __attribute__((address_space(3)))
; __device__ __forceinline__ float bflo(unsigned w) { return __uint_as_float(w << 16); }
; __device__ __forceinline__ float bfhi(unsigned w) { return __uint_as_float(w & 0xffff0000u); }
;     __device__ __forceinline__ void apply4(int row, int col, f32x4 v, const Pre& p) const {
;         const size_t off = (size_t)row * DM + col; const u32x2 bw = p.bw;
;         v = v + (f32x4){bflo(bw.x), bfhi(bw.x), bflo(bw.y), bfhi(bw.y)};
;         if (Xf) *(f32x4*)(Xf + off) = v;
; template <int CT, class Epi> __device__ __forceinline__ void skinny_gemm(LAS unsigned char* lds, const bf16_t* A, const bf16_t* Bt, int N, int K, const Epi& E, int first) {
;     ...
;         if (nsteps >= 4) {
; #pragma unroll 1
;             for (int s0 = 0; s0 < nsteps; s0 += 4) SKINNY_GROUP(4, s0);
;         } else SKINNY_GROUP(2, 0);
;     ...
; #pragma unroll
;         for (int rt = 0; rt < 4; ++rt)
; #pragma unroll
;             for (int ct = 0; ct < CT; ++ct) *(LAS f32x4*)(red + wave * (64 * 16 * CT) + (rt * 16 + r) * (16 * CT) + ct * 16 + 4 * qd) = acc[rt][ct];
;         __syncthreads();
; #pragma unroll
;         for (int e = 0; e < CT / 2; ++e) { const int idx = tid + e * 512, row = idx / (4 * CT), c4 = idx % (4 * CT);
;             f32x4 v = *(const LAS f32x4*)(red + row * (16 * CT) + c4 * 4);
; #pragma unroll
;             for (int w = 1; w < 8; ++w) v = v + *(const LAS f32x4*)(red + w * (64 * 16 * CT) + row * (16 * CT) + c4 * 4);
;             E.apply4(NTOK_P + mt * 64 + row, nt * 16 * CT + c4 * 4, v, pre[e]); }
	ds_read_b128 v[116:119], v242
	ds_read_b128 v[124:127], v242 offset:2048
	ds_read_b128 v[132:135], v242 offset:4096
	ds_read_b128 v[140:143], v242 offset:6144
	ds_read_b128 v[120:123], v243
	ds_read_b128 v[128:131], v243 offset:2048
	ds_read_b128 v[136:139], v243 offset:4096
	ds_read_b128 v[144:147], v243 offset:6144
	ds_read_b128 v[148:151], v244
	ds_read_b128 v[156:159], v244 offset:2048
	ds_read_b128 v[152:155], v245
	ds_read_b128 v[160:163], v245 offset:2048
	s_waitcnt lgkmcnt(0)
	v_mfma_f32_16x16x32_bf16 v[20:23], v[148:151], v[116:119], v[20:23]
	v_mfma_f32_16x16x32_bf16 v[24:27], v[156:159], v[116:119], v[24:27]
	v_mfma_f32_16x16x32_bf16 v[28:31], v[148:151], v[124:127], v[28:31]
	v_mfma_f32_16x16x32_bf16 v[32:35], v[156:159], v[124:127], v[32:35]
	v_mfma_f32_16x16x32_bf16 v[36:39], v[148:151], v[132:135], v[36:39]
	v_mfma_f32_16x16x32_bf16 v[40:43], v[156:159], v[132:135], v[40:43]
	v_mfma_f32_16x16x32_bf16 v[44:47], v[148:151], v[140:143], v[44:47]
	v_mfma_f32_16x16x32_bf16 v[48:51], v[156:159], v[140:143], v[48:51]
	v_mfma_f32_16x16x32_bf16 v[20:23], v[152:155], v[120:123], v[20:23]
	v_mfma_f32_16x16x32_bf16 v[24:27], v[160:163], v[120:123], v[24:27]
	v_mfma_f32_16x16x32_bf16 v[28:31], v[152:155], v[128:131], v[28:31]
	v_mfma_f32_16x16x32_bf16 v[32:35], v[160:163], v[128:131], v[32:35]
	v_mfma_f32_16x16x32_bf16 v[36:39], v[152:155], v[136:139], v[36:39]
	v_mfma_f32_16x16x32_bf16 v[40:43], v[160:163], v[136:139], v[40:43]
	v_mfma_f32_16x16x32_bf16 v[44:47], v[152:155], v[144:147], v[44:47]
	v_mfma_f32_16x16x32_bf16 v[48:51], v[160:163], v[144:147], v[48:51]
	s_add_i32 s4, s4, 4
	s_mov_b64 s[10:11], 0x100
	s_cmp_gt_u32 s4, 11
	v_lshl_add_u64 v[58:59], v[58:59], 0, s[10:11]
	s_cbranch_scc0 .LBB0_1034
	ds_write_b128 v66, v[20:23]
	ds_write_b128 v66, v[24:27] offset:64
	ds_write_b128 v66, v[28:31] offset:2048
	ds_write_b128 v66, v[32:35] offset:2112
	ds_write_b128 v66, v[36:39] offset:4096
	ds_write_b128 v66, v[40:43] offset:4160
	ds_write_b128 v66, v[44:47] offset:6144
	ds_write_b128 v66, v[48:51] offset:6208
	s_waitcnt lgkmcnt(0)
	s_barrier
	ds_read_b128 v[20:23], v64
	ds_read_b128 v[24:27], v64 offset:8192
	ds_read_b128 v[28:31], v64 offset:16384
	ds_read_b128 v[32:35], v64 offset:24576
	s_lshl_b32 s4, s8, 2
	s_andn2_b32 s4, s4, 31
	s_waitcnt lgkmcnt(2)
	v_pk_add_f32 v[22:23], v[22:23], v[26:27]
	v_pk_add_f32 v[24:25], v[20:21], v[24:25]
	s_waitcnt lgkmcnt(1)
	v_pk_add_f32 v[26:27], v[22:23], v[30:31]
	ds_read_b128 v[20:23], v64 offset:32768
	v_pk_add_f32 v[24:25], v[24:25], v[28:29]
	s_waitcnt lgkmcnt(1)
	v_pk_add_f32 v[28:29], v[26:27], v[34:35]
	v_pk_add_f32 v[32:33], v[24:25], v[32:33]
	ds_read_b128 v[24:27], v64 offset:40960
	s_waitcnt lgkmcnt(1)
	v_pk_add_f32 v[34:35], v[28:29], v[22:23]
	ds_read_b128 v[28:31], v64 offset:49152
	v_pk_add_f32 v[32:33], v[32:33], v[20:21]
	ds_read_b128 v[20:23], v64 offset:57344
	s_waitcnt lgkmcnt(2)
	v_pk_add_f32 v[26:27], v[34:35], v[26:27]
	v_pk_add_f32 v[24:25], v[32:33], v[24:25]
	v_add_u32_e32 v36, s4, v63
	s_waitcnt lgkmcnt(1)
	v_pk_add_f32 v[26:27], v[26:27], v[30:31]
	v_pk_add_f32 v[24:25], v[24:25], v[28:29]
	v_ashrrev_i32_e32 v37, 31, v36
	v_lshlrev_b32_e32 v38, 16, v54
	v_and_b32_e32 v39, 0xffff0000, v54
	v_lshlrev_b32_e32 v40, 16, v55
	v_and_b32_e32 v41, 0xffff0000, v55
	s_waitcnt lgkmcnt(0)
	v_pk_add_f32 v[22:23], v[26:27], v[22:23]
	v_pk_add_f32 v[20:21], v[24:25], v[20:21]
	v_lshlrev_b64 v[24:25], 10, v[52:53]
	v_lshl_add_u64 v[24:25], v[24:25], 0, v[36:37]
	v_pk_add_f32 v[22:23], v[22:23], v[40:41]
	v_pk_add_f32 v[20:21], v[20:21], v[38:39]
	s_and_b64 vcc, exec, s[0:1]
	s_cbranch_vccz .LBB0_1037
	v_lshl_add_u64 v[26:27], v[24:25], 2, s[68:69]
	global_store_dwordx4 v[26:27], v[20:23], off

; #define LAS __attribute__((address_space(3)))
; __global__ void __launch_bounds__(512, 2) mk_fwd(Args a) {
;     extern __shared__ __attribute__((aligned(16))) unsigned char lds_raw[];
;     LAS unsigned char* lds = (LAS unsigned char*)lds_raw;
;     cg::grid_group grid = cg::this_grid();
;     const int tid = threadIdx.x, lane = tid & 63, wave = __builtin_amdgcn_readfirstlane(tid >> 6);
;     const int G = gridDim.x, bx = blockIdx.x;
;     unsigned char* ws = a.ws;
;     float* ss = (float*)(ws + WS_SS);
	.amdhsa_kernel _Z6mk_fwd4Args
		.amdhsa_group_segment_fixed_size 0
		.amdhsa_private_segment_fixed_size 0
		.amdhsa_kernarg_size 496
		.amdhsa_user_sgpr_count 2
		.amdhsa_user_sgpr_dispatch_ptr 0
		.amdhsa_user_sgpr_queue_ptr 0
		.amdhsa_user_sgpr_kernarg_segment_ptr 1
		.amdhsa_user_sgpr_dispatch_id 0
		.amdhsa_user_sgpr_kernarg_preload_length 0
		.amdhsa_user_sgpr_kernarg_preload_offset 0
		.amdhsa_user_sgpr_private_segment_size 0
		.amdhsa_uses_dynamic_stack 0
		.amdhsa_enable_private_segment 0
		.amdhsa_system_sgpr_workgroup_id_x 1
		.amdhsa_system_sgpr_workgroup_id_y 0
		.amdhsa_system_sgpr_workgroup_id_z 0
		.amdhsa_system_sgpr_workgroup_info 0
		.amdhsa_system_vgpr_workitem_id 2
		.amdhsa_next_free_vgpr 256
		.amdhsa_next_free_sgpr 102
		.amdhsa_accum_offset 256
		.amdhsa_reserve_vcc 1
		.amdhsa_float_round_mode_32 0
		.amdhsa_float_round_mode_16_64 0
		.amdhsa_float_denorm_mode_32 3
		.amdhsa_float_denorm_mode_16_64 3
		.amdhsa_dx10_clamp 1
		.amdhsa_ieee_mode 1
		.amdhsa_fp16_overflow 0
		.amdhsa_tg_split 0
		.amdhsa_exception_fp_ieee_invalid_op 0
		.amdhsa_exception_fp_denorm_src 0
		.amdhsa_exception_fp_ieee_div_zero 0
		.amdhsa_exception_fp_ieee_overflow 0
		.amdhsa_exception_fp_ieee_underflow 0
		.amdhsa_exception_fp_ieee_inexact 0
		.amdhsa_exception_int_div_zero 0
	.end_amdhsa_kernel

amdhsa.kernels:
  - .agpr_count:     0
    .args:
      - .offset:         0
        .size:           240
        .value_kind:     by_value
      - .offset:         240
        .size:           4
        .value_kind:     hidden_block_count_x
      - .offset:         244
        .size:           4
        .value_kind:     hidden_block_count_y
      - .offset:         248
        .size:           4
        .value_kind:     hidden_block_count_z
      - .offset:         252
        .size:           2
        .value_kind:     hidden_group_size_x
      - .offset:         254
        .size:           2
        .value_kind:     hidden_group_size_y
      - .offset:         256
        .size:           2
        .value_kind:     hidden_group_size_z
      - .offset:         258
        .size:           2
        .value_kind:     hidden_remainder_x
      - .offset:         260
        .size:           2
        .value_kind:     hidden_remainder_y
      - .offset:         262
        .size:           2
        .value_kind:     hidden_remainder_z
      - .offset:         280
        .size:           8
        .value_kind:     hidden_global_offset_x
      - .offset:         288
        .size:           8
        .value_kind:     hidden_global_offset_y
      - .offset:         296
        .size:           8
        .value_kind:     hidden_global_offset_z
      - .offset:         304
        .size:           2
        .value_kind:     hidden_grid_dims
      - .offset:         328
        .size:           8
        .value_kind:     hidden_multigrid_sync_arg
      - .offset:         360
        .size:           4
        .value_kind:     hidden_dynamic_lds_size
    .group_segment_fixed_size: 0
    .kernarg_segment_align: 8
    .kernarg_segment_size: 496
    .language:       OpenCL C
    .language_version:
      - 2
      - 0
    .max_flat_workgroup_size: 512
    .name:           _Z6mk_fwd4Args
    .private_segment_fixed_size: 0
    .sgpr_count:     108
    .sgpr_spill_count: 237
    .symbol:         _Z6mk_fwd4Args.kd
    .uniform_work_group_size: 1
    .uses_dynamic_stack: false
    .vgpr_count:     256
    .vgpr_spill_count: 0
    .wavefront_size: 64
